# layer-1 KV/Q GEMM reduced to 1280 tiles (5 full rounds): the 48 gate columns are computed by otherwise idle workgroups during the compression GEMM phase with a small direct-from-global bf16 MFMA kerne
# speedup vs baseline: 1.0326x; 1.0045x over previous
.LBB0_841:
	v_mov_b32_e32 v8, v136
	s_cmpk_lt_i32 s38, 0x500
	s_cselect_b64 s[10:11], -1, 0
	s_cmpk_gt_i32 s38, 0x4ff
	v_readfirstlane_b32 s0, v8
	s_cbranch_scc1 .LBB0_843
	s_ashr_i32 s4, s38, 31
	s_lshr_b32 s4, s4, 29
	s_add_i32 s4, s38, s4
	s_ashr_i32 s5, s4, 3
	s_and_b32 s4, s4, -8
	s_sub_i32 s4, s38, s4
	s_cmp_lt_i32 s4, 0
	s_movk_i32 s6, 0xa1
	s_cselect_b32 s6, s6, 0xa0
	s_mul_i32 s4, s6, s4
	s_add_i32 s4, s4, s5
	s_mul_hi_i32 s5, s4, 0x66666667
	s_lshr_b32 s6, s5, 31
	s_ashr_i32 s5, s5, 5
	s_add_i32 s5, s5, s6
	s_lshl_b32 s6, s5, 2
	s_mulk_i32 s5, 0x50
	s_sub_i32 s4, s4, s5
	s_bfe_i32 s5, s4, 0x80000
	s_bfe_u32 s5, s5, 0x2000d
	s_add_i32 s5, s4, s5
	s_bfe_i32 s7, s5, 0x80000
	s_and_b32 s5, s5, 0xfc
	s_sub_i32 s4, s4, s5
	s_sext_i32_i16 s7, s7
	s_sext_i32_i8 s4, s4
	s_add_i32 s12, s6, s4
	s_ashr_i32 s80, s7, 2

.LBB0_846:
	s_add_u32 s18, s30, 0x12100000
	s_mov_b64 s[20:21], 0x80
	s_addc_u32 s19, s31, 0
	s_and_b32 s6, s4, 3
	s_add_i32 m0, s90, 0x18000
	v_lshl_add_u64 v[6:7], v[6:7], 0, s[20:21]
	s_lshl_b32 s46, s5, 6
	s_lshl_b32 s7, s5, 13
	s_lshl_b32 s47, s6, 5
	s_lshl_b32 s10, s6, 12
	s_waitcnt vmcnt(4)
	s_barrier
	global_load_lds_dwordx4 v[6:7], off
	v_lshl_add_u64 v[4:5], v[4:5], 0, s[20:21]
	s_add_i32 m0, s90, 0x1a000
	s_add_i32 s8, s90, 0x8000
	s_add_i32 s9, s90, 0xa000
	global_load_lds_dwordx4 v[4:5], off
	v_lshl_add_u64 v[2:3], v[2:3], 0, s[20:21]
	s_mov_b32 m0, s8
	s_add_u32 s4, s16, 0x80080
	global_load_lds_dwordx4 v[2:3], off
	v_lshl_add_u64 v[0:1], v[0:1], 0, s[20:21]
	s_mov_b32 m0, s9
	s_addc_u32 s5, s17, 0
	global_load_lds_dwordx4 v[0:1], off
	s_add_i32 m0, s90, 0x1c000
	v_lshl_add_u64 v[0:1], s[4:5], 0, v[138:139]
	global_load_lds_dwordx4 v[0:1], off
	v_lshl_add_u64 v[0:1], s[4:5], 0, v[140:141]
	s_add_i32 m0, s90, 0x1e000
	s_cmp_eq_u32 s6, 0
	global_load_lds_dwordx4 v[0:1], off
	v_bfe_u32 v0, v8, 4, 2
	v_lshlrev_b32_e32 v144, 2, v0
	v_and_b32_e32 v145, 15, v8
	v_lshlrev_b32_e32 v170, 3, v0
	v_lshlrev_b32_e32 v1, 4, v0
	v_lshlrev_b32_e32 v2, 2, v8
	s_cselect_b64 s[62:63], -1, 0
	v_or_b32_e32 v0, s47, v144
	s_cmp_lt_u32 s6, 2
	v_lshl_or_b32 v1, v145, 6, v1
	v_and_b32_e32 v2, 32, v2
	s_cselect_b64 s[64:65], -1, 0
	s_or_b32 s4, s47, 16
	v_lshlrev_b32_e32 v142, 2, v0
	v_bitop3_b32 v3, v1, s7, v2 bitop3:0xde
	v_bitop3_b32 v171, v1, s10, v2 bitop3:0xde
	s_cmp_lt_u32 s4, 48
	v_lshl_add_u64 v[0:1], s[30:31], 0, v[142:143]
	s_mov_b64 s[4:5], 0x16100000
	v_lshl_add_u64 v[146:147], v[0:1], 0, s[4:5]
	v_lshlrev_b32_e32 v0, 15, v9
	v_and_b32_e32 v0, 0xffff0000, v0
	v_lshl_add_u32 v0, v10, 12, v0
	v_and_b32_e32 v1, 1, v9
	v_lshl_or_b32 v0, v1, 6, v0
	v_lshl_add_u32 v148, v11, 1, v0
	v_lshlrev_b32_e32 v0, 15, v12
	v_and_b32_e32 v0, 0xffff0000, v0
	s_waitcnt vmcnt(6)
	v_lshl_add_u32 v0, v13, 12, v0
	v_and_b32_e32 v1, 1, v12
	s_cselect_b64 s[66:67], -1, 0
	v_lshl_or_b32 v0, v1, 6, v0
	s_add_i32 s6, 16, 0x10000
	s_add_i32 s7, 16, 0x14000
	s_movk_i32 s70, 0xe800
	s_mov_b32 s61, 0
	s_ashr_i32 s56, s38, 31
	v_mov_b32_e32 v149, v143
	v_lshl_add_u32 v150, v14, 1, v0
	v_mov_b32_e32 v151, v143
	v_mov_b64_e32 v[152:153], 0x500
	v_mov_b64_e32 v[154:155], 0x4ff
	v_add_u32_e32 v172, s6, v171
	v_add_u32_e32 v173, 16, v3
	v_add_u32_e32 v174, s7, v171
	v_mov_b32_e32 v175, 0x358637bd
	s_mov_b32 s39, 0x800000
	s_mov_b32 s68, 0x3e0293ee
	s_mov_b32 s71, -1
	s_movk_i32 s4, 0xf000
	s_movk_i32 s5, 0x1fdf
	s_movk_i32 s26, 0x1fef
	s_movk_i32 s27, 0x1fff
	v_mov_b32_e32 v176, 0x1fcf
	s_mov_b32 s44, 0
	s_barrier
	s_branch .LBB0_848

.LBB0_848:
	s_add_i32 s44, s44, 1
	s_mul_i32 s10, s44, s37
	s_mul_hi_u32 s11, s44, s36
	s_add_i32 s11, s11, s10
	s_mul_i32 s10, s44, s36
	s_add_u32 s76, s10, s38
	s_addc_u32 s77, s11, s56
	v_cmp_gt_i64_e64 s[10:11], s[76:77], v[154:155]
	s_and_b64 vcc, exec, s[10:11]
	s_cbranch_vccnz .LBB0_850
	s_ashr_i32 s13, s76, 31
	s_lshr_b32 s13, s13, 29
	s_add_i32 s13, s76, s13
	s_ashr_i32 s45, s13, 3
	s_and_b32 s13, s13, -8
	s_sub_i32 s13, s76, s13
	s_cmp_lt_i32 s13, 0
	s_movk_i32 s60, 0xa1
	s_cselect_b32 s60, s60, 0xa0
	s_mul_i32 s13, s60, s13
	s_add_i32 s13, s13, s45
	s_mul_hi_i32 s45, s13, 0x66666667
	s_lshr_b32 s60, s45, 31
	s_ashr_i32 s45, s45, 5
	s_add_i32 s45, s45, s60
	s_lshl_b32 s60, s45, 2
	s_sub_i32 s72, 64, s60
	s_min_i32 s73, s72, 4
	s_abs_i32 s72, s73
	v_cvt_f32_u32_e32 v0, s72
	s_sub_i32 s75, 0, s72
	s_mulk_i32 s45, 0x50
	s_sub_i32 s13, s13, s45
	v_rcp_iflag_f32_e32 v0, v0
	s_abs_i32 s45, s13
	s_xor_b32 s74, s13, s73
	s_ashr_i32 s74, s74, 31
	v_mul_f32_e32 v0, 0x4f7ffffe, v0
	v_cvt_u32_f32_e32 v0, v0
	s_nop 0
	v_readfirstlane_b32 s78, v0
	s_mul_i32 s75, s75, s78
	s_mul_hi_u32 s75, s78, s75
	s_add_i32 s78, s78, s75
	s_mul_hi_u32 s75, s45, s78
	s_mul_i32 s78, s75, s72
	s_sub_i32 s45, s45, s78
	s_add_i32 s79, s75, 1
	s_sub_i32 s78, s45, s72
	s_cmp_ge_u32 s45, s72
	s_cselect_b32 s75, s79, s75
	s_cselect_b32 s45, s78, s45
	s_add_i32 s78, s75, 1
	s_cmp_ge_u32 s45, s72
	s_cselect_b32 s45, s78, s75
	s_xor_b32 s45, s45, s74
	s_sub_i32 s72, s45, s74
	s_mul_i32 s45, s72, s73
	s_sub_i32 s13, s13, s45
	s_add_i32 s74, s13, s60

.LBB0_1259:
	s_or_b64 exec, exec, s[10:11]
	v_mov_b32_e32 v8, v136
	s_waitcnt lgkmcnt(0)
	s_barrier
	s_cmp_lt_u32 s2, 64
	s_cbranch_scc1 .Lgate_skip
	s_sub_u32 s60, s2, 64
	s_sub_u32 s61, s34, 64
	v_and_b32_e32 v10, 15, v136
	v_bfe_u32 v11, v136, 4, 2
	v_lshrrev_b32_e32 v12, 6, v136
	s_add_u32 s66, s30, 0x17600000
	s_addc_u32 s67, s31, 0
	s_add_u32 s68, s30, 0x1400000
	s_addc_u32 s69, s31, 0
	s_add_u32 s70, s30, 0x24130000
	s_addc_u32 s71, s31, 0
	s_add_u32 s72, s30, 0x16100000
	s_addc_u32 s73, s31, 0
	s_mov_b32 s63, 0x800000
	v_lshlrev_b32_e32 v36, 4, v11
	v_mov_b32_e32 v37, 0
	v_mov_b32_e32 v39, 0
	v_add_u32_e32 v38, 0, v10
	v_lshlrev_b64 v[16:17], 12, v[38:39]
	v_lshl_add_u64 v[16:17], v[16:17], 0, v[36:37]
	v_lshl_add_u64 v[16:17], v[16:17], 0, s[68:69]
	v_add_u32_e32 v38, 16, v10
	v_lshlrev_b64 v[18:19], 12, v[38:39]
	v_lshl_add_u64 v[18:19], v[18:19], 0, v[36:37]
	v_lshl_add_u64 v[18:19], v[18:19], 0, s[68:69]
	v_add_u32_e32 v38, 32, v10
	v_lshlrev_b64 v[20:21], 12, v[38:39]
	v_lshl_add_u64 v[20:21], v[20:21], 0, v[36:37]
	v_lshl_add_u64 v[20:21], v[20:21], 0, s[68:69]
.Lgate_loop:
	s_cmp_ge_u32 s60, 0x80
	s_cbranch_scc1 .Lgate_skip
	s_lshl_b32 s62, s60, 7
	v_lshl_add_u32 v13, v12, 4, s62
	v_add_u32_e32 v38, v13, v10
	v_lshlrev_b64 v[14:15], 12, v[38:39]
	v_lshl_add_u64 v[14:15], v[14:15], 0, v[36:37]
	v_lshl_add_u64 v[14:15], v[14:15], 0, s[66:67]
	global_load_dwordx4 v[40:43], v[14:15], off
	global_load_dwordx4 v[44:47], v[16:17], off
	global_load_dwordx4 v[48:51], v[18:19], off
	global_load_dwordx4 v[52:55], v[20:21], off
	global_load_dwordx4 v[56:59], v[14:15], off offset:64
	global_load_dwordx4 v[60:63], v[16:17], off offset:64
	global_load_dwordx4 v[64:67], v[18:19], off offset:64
	global_load_dwordx4 v[68:71], v[20:21], off offset:64
	global_load_dwordx4 v[72:75], v[14:15], off offset:128
	global_load_dwordx4 v[76:79], v[16:17], off offset:128
	global_load_dwordx4 v[80:83], v[18:19], off offset:128
	global_load_dwordx4 v[84:87], v[20:21], off offset:128
	global_load_dwordx4 v[88:91], v[14:15], off offset:192
	global_load_dwordx4 v[92:95], v[16:17], off offset:192
	global_load_dwordx4 v[96:99], v[18:19], off offset:192
	global_load_dwordx4 v[100:103], v[20:21], off offset:192
	global_load_dwordx4 v[104:107], v[14:15], off offset:256
	global_load_dwordx4 v[108:111], v[16:17], off offset:256
	global_load_dwordx4 v[112:115], v[18:19], off offset:256
	global_load_dwordx4 v[116:119], v[20:21], off offset:256
	global_load_dwordx4 v[120:123], v[14:15], off offset:320
	global_load_dwordx4 v[124:127], v[16:17], off offset:320
	global_load_dwordx4 v[128:131], v[18:19], off offset:320
	global_load_dwordx4 v[132:135], v[20:21], off offset:320
	global_load_dwordx4 v[140:143], v[14:15], off offset:384
	global_load_dwordx4 v[144:147], v[16:17], off offset:384
	global_load_dwordx4 v[148:151], v[18:19], off offset:384
	global_load_dwordx4 v[152:155], v[20:21], off offset:384
	global_load_dwordx4 v[156:159], v[14:15], off offset:448
	global_load_dwordx4 v[160:163], v[16:17], off offset:448
	global_load_dwordx4 v[164:167], v[18:19], off offset:448
	global_load_dwordx4 v[168:171], v[20:21], off offset:448
	s_waitcnt vmcnt(28)
	v_mfma_f32_16x16x32_bf16 v[24:27], v[40:43], v[44:47], 0
	v_mfma_f32_16x16x32_bf16 v[28:31], v[40:43], v[48:51], 0
	v_mfma_f32_16x16x32_bf16 v[32:35], v[40:43], v[52:55], 0
	global_load_dwordx4 v[40:43], v[14:15], off offset:512
	global_load_dwordx4 v[44:47], v[16:17], off offset:512
	global_load_dwordx4 v[48:51], v[18:19], off offset:512
	global_load_dwordx4 v[52:55], v[20:21], off offset:512
	s_waitcnt vmcnt(28)
	v_mfma_f32_16x16x32_bf16 v[24:27], v[56:59], v[60:63], v[24:27]
	v_mfma_f32_16x16x32_bf16 v[28:31], v[56:59], v[64:67], v[28:31]
	v_mfma_f32_16x16x32_bf16 v[32:35], v[56:59], v[68:71], v[32:35]
	global_load_dwordx4 v[56:59], v[14:15], off offset:576
	global_load_dwordx4 v[60:63], v[16:17], off offset:576
	global_load_dwordx4 v[64:67], v[18:19], off offset:576
	global_load_dwordx4 v[68:71], v[20:21], off offset:576
	s_waitcnt vmcnt(28)
	v_mfma_f32_16x16x32_bf16 v[24:27], v[72:75], v[76:79], v[24:27]
	v_mfma_f32_16x16x32_bf16 v[28:31], v[72:75], v[80:83], v[28:31]
	v_mfma_f32_16x16x32_bf16 v[32:35], v[72:75], v[84:87], v[32:35]
	global_load_dwordx4 v[72:75], v[14:15], off offset:640
	global_load_dwordx4 v[76:79], v[16:17], off offset:640
	global_load_dwordx4 v[80:83], v[18:19], off offset:640
	global_load_dwordx4 v[84:87], v[20:21], off offset:640
	s_waitcnt vmcnt(28)
	v_mfma_f32_16x16x32_bf16 v[24:27], v[88:91], v[92:95], v[24:27]
	v_mfma_f32_16x16x32_bf16 v[28:31], v[88:91], v[96:99], v[28:31]
	v_mfma_f32_16x16x32_bf16 v[32:35], v[88:91], v[100:103], v[32:35]
	global_load_dwordx4 v[88:91], v[14:15], off offset:704
	global_load_dwordx4 v[92:95], v[16:17], off offset:704
	global_load_dwordx4 v[96:99], v[18:19], off offset:704
	global_load_dwordx4 v[100:103], v[20:21], off offset:704
	s_waitcnt vmcnt(28)
	v_mfma_f32_16x16x32_bf16 v[24:27], v[104:107], v[108:111], v[24:27]
	v_mfma_f32_16x16x32_bf16 v[28:31], v[104:107], v[112:115], v[28:31]
	v_mfma_f32_16x16x32_bf16 v[32:35], v[104:107], v[116:119], v[32:35]
	global_load_dwordx4 v[104:107], v[14:15], off offset:768
	global_load_dwordx4 v[108:111], v[16:17], off offset:768
	global_load_dwordx4 v[112:115], v[18:19], off offset:768
	global_load_dwordx4 v[116:119], v[20:21], off offset:768
	s_waitcnt vmcnt(28)
	v_mfma_f32_16x16x32_bf16 v[24:27], v[120:123], v[124:127], v[24:27]
	v_mfma_f32_16x16x32_bf16 v[28:31], v[120:123], v[128:131], v[28:31]
	v_mfma_f32_16x16x32_bf16 v[32:35], v[120:123], v[132:135], v[32:35]
	global_load_dwordx4 v[120:123], v[14:15], off offset:832
	global_load_dwordx4 v[124:127], v[16:17], off offset:832
	global_load_dwordx4 v[128:131], v[18:19], off offset:832
	global_load_dwordx4 v[132:135], v[20:21], off offset:832
	s_waitcnt vmcnt(28)
	v_mfma_f32_16x16x32_bf16 v[24:27], v[140:143], v[144:147], v[24:27]
	v_mfma_f32_16x16x32_bf16 v[28:31], v[140:143], v[148:151], v[28:31]
	v_mfma_f32_16x16x32_bf16 v[32:35], v[140:143], v[152:155], v[32:35]
	global_load_dwordx4 v[140:143], v[14:15], off offset:896
	global_load_dwordx4 v[144:147], v[16:17], off offset:896
	global_load_dwordx4 v[148:151], v[18:19], off offset:896
	global_load_dwordx4 v[152:155], v[20:21], off offset:896
	s_waitcnt vmcnt(28)
	v_mfma_f32_16x16x32_bf16 v[24:27], v[156:159], v[160:163], v[24:27]
	v_mfma_f32_16x16x32_bf16 v[28:31], v[156:159], v[164:167], v[28:31]
	v_mfma_f32_16x16x32_bf16 v[32:35], v[156:159], v[168:171], v[32:35]
	global_load_dwordx4 v[156:159], v[14:15], off offset:960
	global_load_dwordx4 v[160:163], v[16:17], off offset:960
	global_load_dwordx4 v[164:167], v[18:19], off offset:960
	global_load_dwordx4 v[168:171], v[20:21], off offset:960
	s_waitcnt vmcnt(28)
	v_mfma_f32_16x16x32_bf16 v[24:27], v[40:43], v[44:47], v[24:27]
	v_mfma_f32_16x16x32_bf16 v[28:31], v[40:43], v[48:51], v[28:31]
	v_mfma_f32_16x16x32_bf16 v[32:35], v[40:43], v[52:55], v[32:35]
	global_load_dwordx4 v[40:43], v[14:15], off offset:1024
	global_load_dwordx4 v[44:47], v[16:17], off offset:1024
	global_load_dwordx4 v[48:51], v[18:19], off offset:1024
	global_load_dwordx4 v[52:55], v[20:21], off offset:1024
	s_waitcnt vmcnt(28)
	v_mfma_f32_16x16x32_bf16 v[24:27], v[56:59], v[60:63], v[24:27]
	v_mfma_f32_16x16x32_bf16 v[28:31], v[56:59], v[64:67], v[28:31]
	v_mfma_f32_16x16x32_bf16 v[32:35], v[56:59], v[68:71], v[32:35]
	global_load_dwordx4 v[56:59], v[14:15], off offset:1088
	global_load_dwordx4 v[60:63], v[16:17], off offset:1088
	global_load_dwordx4 v[64:67], v[18:19], off offset:1088
	global_load_dwordx4 v[68:71], v[20:21], off offset:1088
	s_waitcnt vmcnt(28)
	v_mfma_f32_16x16x32_bf16 v[24:27], v[72:75], v[76:79], v[24:27]
	v_mfma_f32_16x16x32_bf16 v[28:31], v[72:75], v[80:83], v[28:31]
	v_mfma_f32_16x16x32_bf16 v[32:35], v[72:75], v[84:87], v[32:35]
	global_load_dwordx4 v[72:75], v[14:15], off offset:1152
	global_load_dwordx4 v[76:79], v[16:17], off offset:1152
	global_load_dwordx4 v[80:83], v[18:19], off offset:1152
	global_load_dwordx4 v[84:87], v[20:21], off offset:1152
	s_waitcnt vmcnt(28)
	v_mfma_f32_16x16x32_bf16 v[24:27], v[88:91], v[92:95], v[24:27]
	v_mfma_f32_16x16x32_bf16 v[28:31], v[88:91], v[96:99], v[28:31]
	v_mfma_f32_16x16x32_bf16 v[32:35], v[88:91], v[100:103], v[32:35]
	global_load_dwordx4 v[88:91], v[14:15], off offset:1216
	global_load_dwordx4 v[92:95], v[16:17], off offset:1216
	global_load_dwordx4 v[96:99], v[18:19], off offset:1216
	global_load_dwordx4 v[100:103], v[20:21], off offset:1216
	s_waitcnt vmcnt(28)
	v_mfma_f32_16x16x32_bf16 v[24:27], v[104:107], v[108:111], v[24:27]
	v_mfma_f32_16x16x32_bf16 v[28:31], v[104:107], v[112:115], v[28:31]
	v_mfma_f32_16x16x32_bf16 v[32:35], v[104:107], v[116:119], v[32:35]
	global_load_dwordx4 v[104:107], v[14:15], off offset:1280
	global_load_dwordx4 v[108:111], v[16:17], off offset:1280
	global_load_dwordx4 v[112:115], v[18:19], off offset:1280
	global_load_dwordx4 v[116:119], v[20:21], off offset:1280
	s_waitcnt vmcnt(28)
	v_mfma_f32_16x16x32_bf16 v[24:27], v[120:123], v[124:127], v[24:27]
	v_mfma_f32_16x16x32_bf16 v[28:31], v[120:123], v[128:131], v[28:31]
	v_mfma_f32_16x16x32_bf16 v[32:35], v[120:123], v[132:135], v[32:35]
	global_load_dwordx4 v[120:123], v[14:15], off offset:1344
	global_load_dwordx4 v[124:127], v[16:17], off offset:1344
	global_load_dwordx4 v[128:131], v[18:19], off offset:1344
	global_load_dwordx4 v[132:135], v[20:21], off offset:1344
	s_waitcnt vmcnt(28)
	v_mfma_f32_16x16x32_bf16 v[24:27], v[140:143], v[144:147], v[24:27]
	v_mfma_f32_16x16x32_bf16 v[28:31], v[140:143], v[148:151], v[28:31]
	v_mfma_f32_16x16x32_bf16 v[32:35], v[140:143], v[152:155], v[32:35]
	global_load_dwordx4 v[140:143], v[14:15], off offset:1408
	global_load_dwordx4 v[144:147], v[16:17], off offset:1408
	global_load_dwordx4 v[148:151], v[18:19], off offset:1408
	global_load_dwordx4 v[152:155], v[20:21], off offset:1408
	s_waitcnt vmcnt(28)
	v_mfma_f32_16x16x32_bf16 v[24:27], v[156:159], v[160:163], v[24:27]
	v_mfma_f32_16x16x32_bf16 v[28:31], v[156:159], v[164:167], v[28:31]
	v_mfma_f32_16x16x32_bf16 v[32:35], v[156:159], v[168:171], v[32:35]
	global_load_dwordx4 v[156:159], v[14:15], off offset:1472
	global_load_dwordx4 v[160:163], v[16:17], off offset:1472
	global_load_dwordx4 v[164:167], v[18:19], off offset:1472
	global_load_dwordx4 v[168:171], v[20:21], off offset:1472
	s_waitcnt vmcnt(28)
	v_mfma_f32_16x16x32_bf16 v[24:27], v[40:43], v[44:47], v[24:27]
	v_mfma_f32_16x16x32_bf16 v[28:31], v[40:43], v[48:51], v[28:31]
	v_mfma_f32_16x16x32_bf16 v[32:35], v[40:43], v[52:55], v[32:35]
	global_load_dwordx4 v[40:43], v[14:15], off offset:1536
	global_load_dwordx4 v[44:47], v[16:17], off offset:1536
	global_load_dwordx4 v[48:51], v[18:19], off offset:1536
	global_load_dwordx4 v[52:55], v[20:21], off offset:1536
	s_waitcnt vmcnt(28)
	v_mfma_f32_16x16x32_bf16 v[24:27], v[56:59], v[60:63], v[24:27]
	v_mfma_f32_16x16x32_bf16 v[28:31], v[56:59], v[64:67], v[28:31]
	v_mfma_f32_16x16x32_bf16 v[32:35], v[56:59], v[68:71], v[32:35]
	global_load_dwordx4 v[56:59], v[14:15], off offset:1600
	global_load_dwordx4 v[60:63], v[16:17], off offset:1600
	global_load_dwordx4 v[64:67], v[18:19], off offset:1600
	global_load_dwordx4 v[68:71], v[20:21], off offset:1600
	s_waitcnt vmcnt(28)
	v_mfma_f32_16x16x32_bf16 v[24:27], v[72:75], v[76:79], v[24:27]
	v_mfma_f32_16x16x32_bf16 v[28:31], v[72:75], v[80:83], v[28:31]
	v_mfma_f32_16x16x32_bf16 v[32:35], v[72:75], v[84:87], v[32:35]
	global_load_dwordx4 v[72:75], v[14:15], off offset:1664
	global_load_dwordx4 v[76:79], v[16:17], off offset:1664
	global_load_dwordx4 v[80:83], v[18:19], off offset:1664
	global_load_dwordx4 v[84:87], v[20:21], off offset:1664
	s_waitcnt vmcnt(28)
	v_mfma_f32_16x16x32_bf16 v[24:27], v[88:91], v[92:95], v[24:27]
	v_mfma_f32_16x16x32_bf16 v[28:31], v[88:91], v[96:99], v[28:31]
	v_mfma_f32_16x16x32_bf16 v[32:35], v[88:91], v[100:103], v[32:35]
	global_load_dwordx4 v[88:91], v[14:15], off offset:1728
	global_load_dwordx4 v[92:95], v[16:17], off offset:1728
	global_load_dwordx4 v[96:99], v[18:19], off offset:1728
	global_load_dwordx4 v[100:103], v[20:21], off offset:1728
	s_waitcnt vmcnt(28)
	v_mfma_f32_16x16x32_bf16 v[24:27], v[104:107], v[108:111], v[24:27]
	v_mfma_f32_16x16x32_bf16 v[28:31], v[104:107], v[112:115], v[28:31]
	v_mfma_f32_16x16x32_bf16 v[32:35], v[104:107], v[116:119], v[32:35]
	global_load_dwordx4 v[104:107], v[14:15], off offset:1792
	global_load_dwordx4 v[108:111], v[16:17], off offset:1792
	global_load_dwordx4 v[112:115], v[18:19], off offset:1792
	global_load_dwordx4 v[116:119], v[20:21], off offset:1792
	s_waitcnt vmcnt(28)
	v_mfma_f32_16x16x32_bf16 v[24:27], v[120:123], v[124:127], v[24:27]
	v_mfma_f32_16x16x32_bf16 v[28:31], v[120:123], v[128:131], v[28:31]
	v_mfma_f32_16x16x32_bf16 v[32:35], v[120:123], v[132:135], v[32:35]
	global_load_dwordx4 v[120:123], v[14:15], off offset:1856
	global_load_dwordx4 v[124:127], v[16:17], off offset:1856
	global_load_dwordx4 v[128:131], v[18:19], off offset:1856
	global_load_dwordx4 v[132:135], v[20:21], off offset:1856
	s_waitcnt vmcnt(28)
	v_mfma_f32_16x16x32_bf16 v[24:27], v[140:143], v[144:147], v[24:27]
	v_mfma_f32_16x16x32_bf16 v[28:31], v[140:143], v[148:151], v[28:31]
	v_mfma_f32_16x16x32_bf16 v[32:35], v[140:143], v[152:155], v[32:35]
	global_load_dwordx4 v[140:143], v[14:15], off offset:1920
	global_load_dwordx4 v[144:147], v[16:17], off offset:1920
	global_load_dwordx4 v[148:151], v[18:19], off offset:1920
	global_load_dwordx4 v[152:155], v[20:21], off offset:1920
	s_waitcnt vmcnt(28)
	v_mfma_f32_16x16x32_bf16 v[24:27], v[156:159], v[160:163], v[24:27]
	v_mfma_f32_16x16x32_bf16 v[28:31], v[156:159], v[164:167], v[28:31]
	v_mfma_f32_16x16x32_bf16 v[32:35], v[156:159], v[168:171], v[32:35]
	global_load_dwordx4 v[156:159], v[14:15], off offset:1984
	global_load_dwordx4 v[160:163], v[16:17], off offset:1984
	global_load_dwordx4 v[164:167], v[18:19], off offset:1984
	global_load_dwordx4 v[168:171], v[20:21], off offset:1984
	s_waitcnt vmcnt(28)
	v_mfma_f32_16x16x32_bf16 v[24:27], v[40:43], v[44:47], v[24:27]
	v_mfma_f32_16x16x32_bf16 v[28:31], v[40:43], v[48:51], v[28:31]
	v_mfma_f32_16x16x32_bf16 v[32:35], v[40:43], v[52:55], v[32:35]
	global_load_dwordx4 v[40:43], v[14:15], off offset:2048
	global_load_dwordx4 v[44:47], v[16:17], off offset:2048
	global_load_dwordx4 v[48:51], v[18:19], off offset:2048
	global_load_dwordx4 v[52:55], v[20:21], off offset:2048
	s_waitcnt vmcnt(28)
	v_mfma_f32_16x16x32_bf16 v[24:27], v[56:59], v[60:63], v[24:27]
	v_mfma_f32_16x16x32_bf16 v[28:31], v[56:59], v[64:67], v[28:31]
	v_mfma_f32_16x16x32_bf16 v[32:35], v[56:59], v[68:71], v[32:35]
	global_load_dwordx4 v[56:59], v[14:15], off offset:2112
	global_load_dwordx4 v[60:63], v[16:17], off offset:2112
	global_load_dwordx4 v[64:67], v[18:19], off offset:2112
	global_load_dwordx4 v[68:71], v[20:21], off offset:2112
	s_waitcnt vmcnt(28)
	v_mfma_f32_16x16x32_bf16 v[24:27], v[72:75], v[76:79], v[24:27]
	v_mfma_f32_16x16x32_bf16 v[28:31], v[72:75], v[80:83], v[28:31]
	v_mfma_f32_16x16x32_bf16 v[32:35], v[72:75], v[84:87], v[32:35]
	global_load_dwordx4 v[72:75], v[14:15], off offset:2176
	global_load_dwordx4 v[76:79], v[16:17], off offset:2176
	global_load_dwordx4 v[80:83], v[18:19], off offset:2176
	global_load_dwordx4 v[84:87], v[20:21], off offset:2176
	s_waitcnt vmcnt(28)
	v_mfma_f32_16x16x32_bf16 v[24:27], v[88:91], v[92:95], v[24:27]
	v_mfma_f32_16x16x32_bf16 v[28:31], v[88:91], v[96:99], v[28:31]
	v_mfma_f32_16x16x32_bf16 v[32:35], v[88:91], v[100:103], v[32:35]
	global_load_dwordx4 v[88:91], v[14:15], off offset:2240
	global_load_dwordx4 v[92:95], v[16:17], off offset:2240
	global_load_dwordx4 v[96:99], v[18:19], off offset:2240
	global_load_dwordx4 v[100:103], v[20:21], off offset:2240
	s_waitcnt vmcnt(28)
	v_mfma_f32_16x16x32_bf16 v[24:27], v[104:107], v[108:111], v[24:27]
	v_mfma_f32_16x16x32_bf16 v[28:31], v[104:107], v[112:115], v[28:31]
	v_mfma_f32_16x16x32_bf16 v[32:35], v[104:107], v[116:119], v[32:35]
	global_load_dwordx4 v[104:107], v[14:15], off offset:2304
	global_load_dwordx4 v[108:111], v[16:17], off offset:2304
	global_load_dwordx4 v[112:115], v[18:19], off offset:2304
	global_load_dwordx4 v[116:119], v[20:21], off offset:2304
	s_waitcnt vmcnt(28)
	v_mfma_f32_16x16x32_bf16 v[24:27], v[120:123], v[124:127], v[24:27]
	v_mfma_f32_16x16x32_bf16 v[28:31], v[120:123], v[128:131], v[28:31]
	v_mfma_f32_16x16x32_bf16 v[32:35], v[120:123], v[132:135], v[32:35]
	global_load_dwordx4 v[120:123], v[14:15], off offset:2368
	global_load_dwordx4 v[124:127], v[16:17], off offset:2368
	global_load_dwordx4 v[128:131], v[18:19], off offset:2368
	global_load_dwordx4 v[132:135], v[20:21], off offset:2368
	s_waitcnt vmcnt(28)
	v_mfma_f32_16x16x32_bf16 v[24:27], v[140:143], v[144:147], v[24:27]
	v_mfma_f32_16x16x32_bf16 v[28:31], v[140:143], v[148:151], v[28:31]
	v_mfma_f32_16x16x32_bf16 v[32:35], v[140:143], v[152:155], v[32:35]
	global_load_dwordx4 v[140:143], v[14:15], off offset:2432
	global_load_dwordx4 v[144:147], v[16:17], off offset:2432
	global_load_dwordx4 v[148:151], v[18:19], off offset:2432
	global_load_dwordx4 v[152:155], v[20:21], off offset:2432
	s_waitcnt vmcnt(28)
	v_mfma_f32_16x16x32_bf16 v[24:27], v[156:159], v[160:163], v[24:27]
	v_mfma_f32_16x16x32_bf16 v[28:31], v[156:159], v[164:167], v[28:31]
	v_mfma_f32_16x16x32_bf16 v[32:35], v[156:159], v[168:171], v[32:35]
	global_load_dwordx4 v[156:159], v[14:15], off offset:2496
	global_load_dwordx4 v[160:163], v[16:17], off offset:2496
	global_load_dwordx4 v[164:167], v[18:19], off offset:2496
	global_load_dwordx4 v[168:171], v[20:21], off offset:2496
	s_waitcnt vmcnt(28)
	v_mfma_f32_16x16x32_bf16 v[24:27], v[40:43], v[44:47], v[24:27]
	v_mfma_f32_16x16x32_bf16 v[28:31], v[40:43], v[48:51], v[28:31]
	v_mfma_f32_16x16x32_bf16 v[32:35], v[40:43], v[52:55], v[32:35]
	global_load_dwordx4 v[40:43], v[14:15], off offset:2560
	global_load_dwordx4 v[44:47], v[16:17], off offset:2560
	global_load_dwordx4 v[48:51], v[18:19], off offset:2560
	global_load_dwordx4 v[52:55], v[20:21], off offset:2560
	s_waitcnt vmcnt(28)
	v_mfma_f32_16x16x32_bf16 v[24:27], v[56:59], v[60:63], v[24:27]
	v_mfma_f32_16x16x32_bf16 v[28:31], v[56:59], v[64:67], v[28:31]
	v_mfma_f32_16x16x32_bf16 v[32:35], v[56:59], v[68:71], v[32:35]
	global_load_dwordx4 v[56:59], v[14:15], off offset:2624
	global_load_dwordx4 v[60:63], v[16:17], off offset:2624
	global_load_dwordx4 v[64:67], v[18:19], off offset:2624
	global_load_dwordx4 v[68:71], v[20:21], off offset:2624
	s_waitcnt vmcnt(28)
	v_mfma_f32_16x16x32_bf16 v[24:27], v[72:75], v[76:79], v[24:27]
	v_mfma_f32_16x16x32_bf16 v[28:31], v[72:75], v[80:83], v[28:31]
	v_mfma_f32_16x16x32_bf16 v[32:35], v[72:75], v[84:87], v[32:35]
	global_load_dwordx4 v[72:75], v[14:15], off offset:2688
	global_load_dwordx4 v[76:79], v[16:17], off offset:2688
	global_load_dwordx4 v[80:83], v[18:19], off offset:2688
	global_load_dwordx4 v[84:87], v[20:21], off offset:2688
	s_waitcnt vmcnt(28)
	v_mfma_f32_16x16x32_bf16 v[24:27], v[88:91], v[92:95], v[24:27]
	v_mfma_f32_16x16x32_bf16 v[28:31], v[88:91], v[96:99], v[28:31]
	v_mfma_f32_16x16x32_bf16 v[32:35], v[88:91], v[100:103], v[32:35]
	global_load_dwordx4 v[88:91], v[14:15], off offset:2752
	global_load_dwordx4 v[92:95], v[16:17], off offset:2752
	global_load_dwordx4 v[96:99], v[18:19], off offset:2752
	global_load_dwordx4 v[100:103], v[20:21], off offset:2752
	s_waitcnt vmcnt(28)
	v_mfma_f32_16x16x32_bf16 v[24:27], v[104:107], v[108:111], v[24:27]
	v_mfma_f32_16x16x32_bf16 v[28:31], v[104:107], v[112:115], v[28:31]
	v_mfma_f32_16x16x32_bf16 v[32:35], v[104:107], v[116:119], v[32:35]
	global_load_dwordx4 v[104:107], v[14:15], off offset:2816
	global_load_dwordx4 v[108:111], v[16:17], off offset:2816
	global_load_dwordx4 v[112:115], v[18:19], off offset:2816
	global_load_dwordx4 v[116:119], v[20:21], off offset:2816
	s_waitcnt vmcnt(28)
	v_mfma_f32_16x16x32_bf16 v[24:27], v[120:123], v[124:127], v[24:27]
	v_mfma_f32_16x16x32_bf16 v[28:31], v[120:123], v[128:131], v[28:31]
	v_mfma_f32_16x16x32_bf16 v[32:35], v[120:123], v[132:135], v[32:35]
	global_load_dwordx4 v[120:123], v[14:15], off offset:2880
	global_load_dwordx4 v[124:127], v[16:17], off offset:2880
	global_load_dwordx4 v[128:131], v[18:19], off offset:2880
	global_load_dwordx4 v[132:135], v[20:21], off offset:2880
	s_waitcnt vmcnt(28)
	v_mfma_f32_16x16x32_bf16 v[24:27], v[140:143], v[144:147], v[24:27]
	v_mfma_f32_16x16x32_bf16 v[28:31], v[140:143], v[148:151], v[28:31]
	v_mfma_f32_16x16x32_bf16 v[32:35], v[140:143], v[152:155], v[32:35]
	global_load_dwordx4 v[140:143], v[14:15], off offset:2944
	global_load_dwordx4 v[144:147], v[16:17], off offset:2944
	global_load_dwordx4 v[148:151], v[18:19], off offset:2944
	global_load_dwordx4 v[152:155], v[20:21], off offset:2944
	s_waitcnt vmcnt(28)
	v_mfma_f32_16x16x32_bf16 v[24:27], v[156:159], v[160:163], v[24:27]
	v_mfma_f32_16x16x32_bf16 v[28:31], v[156:159], v[164:167], v[28:31]
	v_mfma_f32_16x16x32_bf16 v[32:35], v[156:159], v[168:171], v[32:35]
	global_load_dwordx4 v[156:159], v[14:15], off offset:3008
	global_load_dwordx4 v[160:163], v[16:17], off offset:3008
	global_load_dwordx4 v[164:167], v[18:19], off offset:3008
	global_load_dwordx4 v[168:171], v[20:21], off offset:3008
	s_waitcnt vmcnt(28)
	v_mfma_f32_16x16x32_bf16 v[24:27], v[40:43], v[44:47], v[24:27]
	v_mfma_f32_16x16x32_bf16 v[28:31], v[40:43], v[48:51], v[28:31]
	v_mfma_f32_16x16x32_bf16 v[32:35], v[40:43], v[52:55], v[32:35]
	global_load_dwordx4 v[40:43], v[14:15], off offset:3072
	global_load_dwordx4 v[44:47], v[16:17], off offset:3072
	global_load_dwordx4 v[48:51], v[18:19], off offset:3072
	global_load_dwordx4 v[52:55], v[20:21], off offset:3072
	s_waitcnt vmcnt(28)
	v_mfma_f32_16x16x32_bf16 v[24:27], v[56:59], v[60:63], v[24:27]
	v_mfma_f32_16x16x32_bf16 v[28:31], v[56:59], v[64:67], v[28:31]
	v_mfma_f32_16x16x32_bf16 v[32:35], v[56:59], v[68:71], v[32:35]
	global_load_dwordx4 v[56:59], v[14:15], off offset:3136
	global_load_dwordx4 v[60:63], v[16:17], off offset:3136
	global_load_dwordx4 v[64:67], v[18:19], off offset:3136
	global_load_dwordx4 v[68:71], v[20:21], off offset:3136
	s_waitcnt vmcnt(28)
	v_mfma_f32_16x16x32_bf16 v[24:27], v[72:75], v[76:79], v[24:27]
	v_mfma_f32_16x16x32_bf16 v[28:31], v[72:75], v[80:83], v[28:31]
	v_mfma_f32_16x16x32_bf16 v[32:35], v[72:75], v[84:87], v[32:35]
	global_load_dwordx4 v[72:75], v[14:15], off offset:3200
	global_load_dwordx4 v[76:79], v[16:17], off offset:3200
	global_load_dwordx4 v[80:83], v[18:19], off offset:3200
	global_load_dwordx4 v[84:87], v[20:21], off offset:3200
	s_waitcnt vmcnt(28)
	v_mfma_f32_16x16x32_bf16 v[24:27], v[88:91], v[92:95], v[24:27]
	v_mfma_f32_16x16x32_bf16 v[28:31], v[88:91], v[96:99], v[28:31]
	v_mfma_f32_16x16x32_bf16 v[32:35], v[88:91], v[100:103], v[32:35]
	global_load_dwordx4 v[88:91], v[14:15], off offset:3264
	global_load_dwordx4 v[92:95], v[16:17], off offset:3264
	global_load_dwordx4 v[96:99], v[18:19], off offset:3264
	global_load_dwordx4 v[100:103], v[20:21], off offset:3264
	s_waitcnt vmcnt(28)
	v_mfma_f32_16x16x32_bf16 v[24:27], v[104:107], v[108:111], v[24:27]
	v_mfma_f32_16x16x32_bf16 v[28:31], v[104:107], v[112:115], v[28:31]
	v_mfma_f32_16x16x32_bf16 v[32:35], v[104:107], v[116:119], v[32:35]
	global_load_dwordx4 v[104:107], v[14:15], off offset:3328
	global_load_dwordx4 v[108:111], v[16:17], off offset:3328
	global_load_dwordx4 v[112:115], v[18:19], off offset:3328
	global_load_dwordx4 v[116:119], v[20:21], off offset:3328
	s_waitcnt vmcnt(28)
	v_mfma_f32_16x16x32_bf16 v[24:27], v[120:123], v[124:127], v[24:27]
	v_mfma_f32_16x16x32_bf16 v[28:31], v[120:123], v[128:131], v[28:31]
	v_mfma_f32_16x16x32_bf16 v[32:35], v[120:123], v[132:135], v[32:35]
	global_load_dwordx4 v[120:123], v[14:15], off offset:3392
	global_load_dwordx4 v[124:127], v[16:17], off offset:3392
	global_load_dwordx4 v[128:131], v[18:19], off offset:3392
	global_load_dwordx4 v[132:135], v[20:21], off offset:3392
	s_waitcnt vmcnt(28)
	v_mfma_f32_16x16x32_bf16 v[24:27], v[140:143], v[144:147], v[24:27]
	v_mfma_f32_16x16x32_bf16 v[28:31], v[140:143], v[148:151], v[28:31]
	v_mfma_f32_16x16x32_bf16 v[32:35], v[140:143], v[152:155], v[32:35]
	global_load_dwordx4 v[140:143], v[14:15], off offset:3456
	global_load_dwordx4 v[144:147], v[16:17], off offset:3456
	global_load_dwordx4 v[148:151], v[18:19], off offset:3456
	global_load_dwordx4 v[152:155], v[20:21], off offset:3456
	s_waitcnt vmcnt(28)
	v_mfma_f32_16x16x32_bf16 v[24:27], v[156:159], v[160:163], v[24:27]
	v_mfma_f32_16x16x32_bf16 v[28:31], v[156:159], v[164:167], v[28:31]
	v_mfma_f32_16x16x32_bf16 v[32:35], v[156:159], v[168:171], v[32:35]
	global_load_dwordx4 v[156:159], v[14:15], off offset:3520
	global_load_dwordx4 v[160:163], v[16:17], off offset:3520
	global_load_dwordx4 v[164:167], v[18:19], off offset:3520
	global_load_dwordx4 v[168:171], v[20:21], off offset:3520
	s_waitcnt vmcnt(28)
	v_mfma_f32_16x16x32_bf16 v[24:27], v[40:43], v[44:47], v[24:27]
	v_mfma_f32_16x16x32_bf16 v[28:31], v[40:43], v[48:51], v[28:31]
	v_mfma_f32_16x16x32_bf16 v[32:35], v[40:43], v[52:55], v[32:35]
	global_load_dwordx4 v[40:43], v[14:15], off offset:3584
	global_load_dwordx4 v[44:47], v[16:17], off offset:3584
	global_load_dwordx4 v[48:51], v[18:19], off offset:3584
	global_load_dwordx4 v[52:55], v[20:21], off offset:3584
	s_waitcnt vmcnt(28)
	v_mfma_f32_16x16x32_bf16 v[24:27], v[56:59], v[60:63], v[24:27]
	v_mfma_f32_16x16x32_bf16 v[28:31], v[56:59], v[64:67], v[28:31]
	v_mfma_f32_16x16x32_bf16 v[32:35], v[56:59], v[68:71], v[32:35]
	global_load_dwordx4 v[56:59], v[14:15], off offset:3648
	global_load_dwordx4 v[60:63], v[16:17], off offset:3648
	global_load_dwordx4 v[64:67], v[18:19], off offset:3648
	global_load_dwordx4 v[68:71], v[20:21], off offset:3648
	s_waitcnt vmcnt(28)
	v_mfma_f32_16x16x32_bf16 v[24:27], v[72:75], v[76:79], v[24:27]
	v_mfma_f32_16x16x32_bf16 v[28:31], v[72:75], v[80:83], v[28:31]
	v_mfma_f32_16x16x32_bf16 v[32:35], v[72:75], v[84:87], v[32:35]
	global_load_dwordx4 v[72:75], v[14:15], off offset:3712
	global_load_dwordx4 v[76:79], v[16:17], off offset:3712
	global_load_dwordx4 v[80:83], v[18:19], off offset:3712
	global_load_dwordx4 v[84:87], v[20:21], off offset:3712
	s_waitcnt vmcnt(28)
	v_mfma_f32_16x16x32_bf16 v[24:27], v[88:91], v[92:95], v[24:27]
	v_mfma_f32_16x16x32_bf16 v[28:31], v[88:91], v[96:99], v[28:31]
	v_mfma_f32_16x16x32_bf16 v[32:35], v[88:91], v[100:103], v[32:35]
	global_load_dwordx4 v[88:91], v[14:15], off offset:3776
	global_load_dwordx4 v[92:95], v[16:17], off offset:3776
	global_load_dwordx4 v[96:99], v[18:19], off offset:3776
	global_load_dwordx4 v[100:103], v[20:21], off offset:3776
	s_waitcnt vmcnt(28)
	v_mfma_f32_16x16x32_bf16 v[24:27], v[104:107], v[108:111], v[24:27]
	v_mfma_f32_16x16x32_bf16 v[28:31], v[104:107], v[112:115], v[28:31]
	v_mfma_f32_16x16x32_bf16 v[32:35], v[104:107], v[116:119], v[32:35]
	global_load_dwordx4 v[104:107], v[14:15], off offset:3840
	global_load_dwordx4 v[108:111], v[16:17], off offset:3840
	global_load_dwordx4 v[112:115], v[18:19], off offset:3840
	global_load_dwordx4 v[116:119], v[20:21], off offset:3840
	s_waitcnt vmcnt(28)
	v_mfma_f32_16x16x32_bf16 v[24:27], v[120:123], v[124:127], v[24:27]
	v_mfma_f32_16x16x32_bf16 v[28:31], v[120:123], v[128:131], v[28:31]
	v_mfma_f32_16x16x32_bf16 v[32:35], v[120:123], v[132:135], v[32:35]
	global_load_dwordx4 v[120:123], v[14:15], off offset:3904
	global_load_dwordx4 v[124:127], v[16:17], off offset:3904
	global_load_dwordx4 v[128:131], v[18:19], off offset:3904
	global_load_dwordx4 v[132:135], v[20:21], off offset:3904
	s_waitcnt vmcnt(28)
	v_mfma_f32_16x16x32_bf16 v[24:27], v[140:143], v[144:147], v[24:27]
	v_mfma_f32_16x16x32_bf16 v[28:31], v[140:143], v[148:151], v[28:31]
	v_mfma_f32_16x16x32_bf16 v[32:35], v[140:143], v[152:155], v[32:35]
	global_load_dwordx4 v[140:143], v[14:15], off offset:3968
	global_load_dwordx4 v[144:147], v[16:17], off offset:3968
	global_load_dwordx4 v[148:151], v[18:19], off offset:3968
	global_load_dwordx4 v[152:155], v[20:21], off offset:3968
	s_waitcnt vmcnt(28)
	v_mfma_f32_16x16x32_bf16 v[24:27], v[156:159], v[160:163], v[24:27]
	v_mfma_f32_16x16x32_bf16 v[28:31], v[156:159], v[164:167], v[28:31]
	v_mfma_f32_16x16x32_bf16 v[32:35], v[156:159], v[168:171], v[32:35]
	global_load_dwordx4 v[156:159], v[14:15], off offset:4032
	global_load_dwordx4 v[160:163], v[16:17], off offset:4032
	global_load_dwordx4 v[164:167], v[18:19], off offset:4032
	global_load_dwordx4 v[168:171], v[20:21], off offset:4032
	s_waitcnt vmcnt(28)
	v_mfma_f32_16x16x32_bf16 v[24:27], v[40:43], v[44:47], v[24:27]
	v_mfma_f32_16x16x32_bf16 v[28:31], v[40:43], v[48:51], v[28:31]
	v_mfma_f32_16x16x32_bf16 v[32:35], v[40:43], v[52:55], v[32:35]
	s_waitcnt vmcnt(24)
	v_mfma_f32_16x16x32_bf16 v[24:27], v[56:59], v[60:63], v[24:27]
	v_mfma_f32_16x16x32_bf16 v[28:31], v[56:59], v[64:67], v[28:31]
	v_mfma_f32_16x16x32_bf16 v[32:35], v[56:59], v[68:71], v[32:35]
	s_waitcnt vmcnt(20)
	v_mfma_f32_16x16x32_bf16 v[24:27], v[72:75], v[76:79], v[24:27]
	v_mfma_f32_16x16x32_bf16 v[28:31], v[72:75], v[80:83], v[28:31]
	v_mfma_f32_16x16x32_bf16 v[32:35], v[72:75], v[84:87], v[32:35]
	s_waitcnt vmcnt(16)
	v_mfma_f32_16x16x32_bf16 v[24:27], v[88:91], v[92:95], v[24:27]
	v_mfma_f32_16x16x32_bf16 v[28:31], v[88:91], v[96:99], v[28:31]
	v_mfma_f32_16x16x32_bf16 v[32:35], v[88:91], v[100:103], v[32:35]
	s_waitcnt vmcnt(12)
	v_mfma_f32_16x16x32_bf16 v[24:27], v[104:107], v[108:111], v[24:27]
	v_mfma_f32_16x16x32_bf16 v[28:31], v[104:107], v[112:115], v[28:31]
	v_mfma_f32_16x16x32_bf16 v[32:35], v[104:107], v[116:119], v[32:35]
	s_waitcnt vmcnt(8)
	v_mfma_f32_16x16x32_bf16 v[24:27], v[120:123], v[124:127], v[24:27]
	v_mfma_f32_16x16x32_bf16 v[28:31], v[120:123], v[128:131], v[28:31]
	v_mfma_f32_16x16x32_bf16 v[32:35], v[120:123], v[132:135], v[32:35]
	s_waitcnt vmcnt(4)
	v_mfma_f32_16x16x32_bf16 v[24:27], v[140:143], v[144:147], v[24:27]
	v_mfma_f32_16x16x32_bf16 v[28:31], v[140:143], v[148:151], v[28:31]
	v_mfma_f32_16x16x32_bf16 v[32:35], v[140:143], v[152:155], v[32:35]
	s_waitcnt vmcnt(0)
	v_mfma_f32_16x16x32_bf16 v[24:27], v[156:159], v[160:163], v[24:27]
	v_mfma_f32_16x16x32_bf16 v[28:31], v[156:159], v[164:167], v[28:31]
	v_mfma_f32_16x16x32_bf16 v[32:35], v[156:159], v[168:171], v[32:35]
	v_lshl_add_u32 v38, v11, 2, v13
	v_lshl_add_u64 v[168:169], v[38:39], 2, s[70:71]
	global_load_dwordx4 v[172:175], v[168:169], off
	v_mov_b32_e32 v176, 0x358637bd
	v_mul_u32_u24_e32 v170, 0xc0, v38
	v_lshl_add_u32 v170, v10, 2, v170
	v_mov_b32_e32 v171, 0
	v_lshl_add_u64 v[180:181], v[170:171], 0, s[72:73]
	s_waitcnt vmcnt(0)
	v_fmamk_f32 v172, v172, 0x3a000000, v176
	v_mul_f32_e32 v177, 0x4b800000, v172
	v_cmp_gt_f32_e32 vcc, s63, v172
	s_nop 1
	v_cndmask_b32_e32 v172, v172, v177, vcc
	v_rsq_f32_e32 v172, v172
	s_nop 0
	v_mul_f32_e32 v177, 0x45800000, v172
	v_cndmask_b32_e32 v172, v172, v177, vcc
	v_fmamk_f32 v173, v173, 0x3a000000, v176
	v_mul_f32_e32 v177, 0x4b800000, v173
	v_cmp_gt_f32_e32 vcc, s63, v173
	s_nop 1
	v_cndmask_b32_e32 v173, v173, v177, vcc
	v_rsq_f32_e32 v173, v173
	s_nop 0
	v_mul_f32_e32 v177, 0x45800000, v173
	v_cndmask_b32_e32 v173, v173, v177, vcc
	v_fmamk_f32 v174, v174, 0x3a000000, v176
	v_mul_f32_e32 v177, 0x4b800000, v174
	v_cmp_gt_f32_e32 vcc, s63, v174
	s_nop 1
	v_cndmask_b32_e32 v174, v174, v177, vcc
	v_rsq_f32_e32 v174, v174
	s_nop 0
	v_mul_f32_e32 v177, 0x45800000, v174
	v_cndmask_b32_e32 v174, v174, v177, vcc
	v_fmamk_f32 v175, v175, 0x3a000000, v176
	v_mul_f32_e32 v177, 0x4b800000, v175
	v_cmp_gt_f32_e32 vcc, s63, v175
	s_nop 1
	v_cndmask_b32_e32 v175, v175, v177, vcc
	v_rsq_f32_e32 v175, v175
	s_nop 0
	v_mul_f32_e32 v177, 0x45800000, v175
	v_cndmask_b32_e32 v175, v175, v177, vcc
	v_mul_f32_e32 v24, v24, v172
	v_mul_f32_e32 v24, 0xbfb8aa3b, v24
	v_exp_f32_e32 v24, v24
	s_nop 0
	v_add_f32_e32 v24, 1.0, v24
	v_div_scale_f32 v184, s[64:65], v24, v24, 1.0
	v_rcp_f32_e32 v185, v184
	s_nop 0
	v_fma_f32 v186, -v184, v185, 1.0
	v_fmac_f32_e32 v185, v186, v185
	v_div_scale_f32 v186, vcc, 1.0, v24, 1.0
	v_mul_f32_e32 v187, v186, v185
	v_fma_f32 v188, -v184, v187, v186
	v_fmac_f32_e32 v187, v188, v185
	v_fma_f32 v184, -v184, v187, v186
	v_div_fmas_f32 v184, v184, v185, v187
	v_div_fixup_f32 v24, v184, v24, 1.0
	global_store_dword v[180:181], v24, off offset:0
	v_mul_f32_e32 v25, v25, v173
	v_mul_f32_e32 v25, 0xbfb8aa3b, v25
	v_exp_f32_e32 v25, v25
	s_nop 0
	v_add_f32_e32 v25, 1.0, v25
	v_div_scale_f32 v184, s[64:65], v25, v25, 1.0
	v_rcp_f32_e32 v185, v184
	s_nop 0
	v_fma_f32 v186, -v184, v185, 1.0
	v_fmac_f32_e32 v185, v186, v185
	v_div_scale_f32 v186, vcc, 1.0, v25, 1.0
	v_mul_f32_e32 v187, v186, v185
	v_fma_f32 v188, -v184, v187, v186
	v_fmac_f32_e32 v187, v188, v185
	v_fma_f32 v184, -v184, v187, v186
	v_div_fmas_f32 v184, v184, v185, v187
	v_div_fixup_f32 v25, v184, v25, 1.0
	global_store_dword v[180:181], v25, off offset:192
	v_mul_f32_e32 v26, v26, v174
	v_mul_f32_e32 v26, 0xbfb8aa3b, v26
	v_exp_f32_e32 v26, v26
	s_nop 0
	v_add_f32_e32 v26, 1.0, v26
	v_div_scale_f32 v184, s[64:65], v26, v26, 1.0
	v_rcp_f32_e32 v185, v184
	s_nop 0
	v_fma_f32 v186, -v184, v185, 1.0
	v_fmac_f32_e32 v185, v186, v185
	v_div_scale_f32 v186, vcc, 1.0, v26, 1.0
	v_mul_f32_e32 v187, v186, v185
	v_fma_f32 v188, -v184, v187, v186
	v_fmac_f32_e32 v187, v188, v185
	v_fma_f32 v184, -v184, v187, v186
	v_div_fmas_f32 v184, v184, v185, v187
	v_div_fixup_f32 v26, v184, v26, 1.0
	global_store_dword v[180:181], v26, off offset:384
	v_mul_f32_e32 v27, v27, v175
	v_mul_f32_e32 v27, 0xbfb8aa3b, v27
	v_exp_f32_e32 v27, v27
	s_nop 0
	v_add_f32_e32 v27, 1.0, v27
	v_div_scale_f32 v184, s[64:65], v27, v27, 1.0
	v_rcp_f32_e32 v185, v184
	s_nop 0
	v_fma_f32 v186, -v184, v185, 1.0
	v_fmac_f32_e32 v185, v186, v185
	v_div_scale_f32 v186, vcc, 1.0, v27, 1.0
	v_mul_f32_e32 v187, v186, v185
	v_fma_f32 v188, -v184, v187, v186
	v_fmac_f32_e32 v187, v188, v185
	v_fma_f32 v184, -v184, v187, v186
	v_div_fmas_f32 v184, v184, v185, v187
	v_div_fixup_f32 v27, v184, v27, 1.0
	global_store_dword v[180:181], v27, off offset:576
	v_mul_f32_e32 v28, v28, v172
	v_mul_f32_e32 v28, 0xbfb8aa3b, v28
	v_exp_f32_e32 v28, v28
	s_nop 0
	v_add_f32_e32 v28, 1.0, v28
	v_div_scale_f32 v184, s[64:65], v28, v28, 1.0
	v_rcp_f32_e32 v185, v184
	s_nop 0
	v_fma_f32 v186, -v184, v185, 1.0
	v_fmac_f32_e32 v185, v186, v185
	v_div_scale_f32 v186, vcc, 1.0, v28, 1.0
	v_mul_f32_e32 v187, v186, v185
	v_fma_f32 v188, -v184, v187, v186
	v_fmac_f32_e32 v187, v188, v185
	v_fma_f32 v184, -v184, v187, v186
	v_div_fmas_f32 v184, v184, v185, v187
	v_div_fixup_f32 v28, v184, v28, 1.0
	global_store_dword v[180:181], v28, off offset:64
	v_mul_f32_e32 v29, v29, v173
	v_mul_f32_e32 v29, 0xbfb8aa3b, v29
	v_exp_f32_e32 v29, v29
	s_nop 0
	v_add_f32_e32 v29, 1.0, v29
	v_div_scale_f32 v184, s[64:65], v29, v29, 1.0
	v_rcp_f32_e32 v185, v184
	s_nop 0
	v_fma_f32 v186, -v184, v185, 1.0
	v_fmac_f32_e32 v185, v186, v185
	v_div_scale_f32 v186, vcc, 1.0, v29, 1.0
	v_mul_f32_e32 v187, v186, v185
	v_fma_f32 v188, -v184, v187, v186
	v_fmac_f32_e32 v187, v188, v185
	v_fma_f32 v184, -v184, v187, v186
	v_div_fmas_f32 v184, v184, v185, v187
	v_div_fixup_f32 v29, v184, v29, 1.0
	global_store_dword v[180:181], v29, off offset:256
	v_mul_f32_e32 v30, v30, v174
	v_mul_f32_e32 v30, 0xbfb8aa3b, v30
	v_exp_f32_e32 v30, v30
	s_nop 0
	v_add_f32_e32 v30, 1.0, v30
	v_div_scale_f32 v184, s[64:65], v30, v30, 1.0
	v_rcp_f32_e32 v185, v184
	s_nop 0
	v_fma_f32 v186, -v184, v185, 1.0
	v_fmac_f32_e32 v185, v186, v185
	v_div_scale_f32 v186, vcc, 1.0, v30, 1.0
	v_mul_f32_e32 v187, v186, v185
	v_fma_f32 v188, -v184, v187, v186
	v_fmac_f32_e32 v187, v188, v185
	v_fma_f32 v184, -v184, v187, v186
	v_div_fmas_f32 v184, v184, v185, v187
	v_div_fixup_f32 v30, v184, v30, 1.0
	global_store_dword v[180:181], v30, off offset:448
	v_mul_f32_e32 v31, v31, v175
	v_mul_f32_e32 v31, 0xbfb8aa3b, v31
	v_exp_f32_e32 v31, v31
	s_nop 0
	v_add_f32_e32 v31, 1.0, v31
	v_div_scale_f32 v184, s[64:65], v31, v31, 1.0
	v_rcp_f32_e32 v185, v184
	s_nop 0
	v_fma_f32 v186, -v184, v185, 1.0
	v_fmac_f32_e32 v185, v186, v185
	v_div_scale_f32 v186, vcc, 1.0, v31, 1.0
	v_mul_f32_e32 v187, v186, v185
	v_fma_f32 v188, -v184, v187, v186
	v_fmac_f32_e32 v187, v188, v185
	v_fma_f32 v184, -v184, v187, v186
	v_div_fmas_f32 v184, v184, v185, v187
	v_div_fixup_f32 v31, v184, v31, 1.0
	global_store_dword v[180:181], v31, off offset:640
	v_mul_f32_e32 v32, v32, v172
	v_mul_f32_e32 v32, 0xbfb8aa3b, v32
	v_exp_f32_e32 v32, v32
	s_nop 0
	v_add_f32_e32 v32, 1.0, v32
	v_div_scale_f32 v184, s[64:65], v32, v32, 1.0
	v_rcp_f32_e32 v185, v184
	s_nop 0
	v_fma_f32 v186, -v184, v185, 1.0
	v_fmac_f32_e32 v185, v186, v185
	v_div_scale_f32 v186, vcc, 1.0, v32, 1.0
	v_mul_f32_e32 v187, v186, v185
	v_fma_f32 v188, -v184, v187, v186
	v_fmac_f32_e32 v187, v188, v185
	v_fma_f32 v184, -v184, v187, v186
	v_div_fmas_f32 v184, v184, v185, v187
	v_div_fixup_f32 v32, v184, v32, 1.0
	global_store_dword v[180:181], v32, off offset:128
	v_mul_f32_e32 v33, v33, v173
	v_mul_f32_e32 v33, 0xbfb8aa3b, v33
	v_exp_f32_e32 v33, v33
	s_nop 0
	v_add_f32_e32 v33, 1.0, v33
	v_div_scale_f32 v184, s[64:65], v33, v33, 1.0
	v_rcp_f32_e32 v185, v184
	s_nop 0
	v_fma_f32 v186, -v184, v185, 1.0
	v_fmac_f32_e32 v185, v186, v185
	v_div_scale_f32 v186, vcc, 1.0, v33, 1.0
	v_mul_f32_e32 v187, v186, v185
	v_fma_f32 v188, -v184, v187, v186
	v_fmac_f32_e32 v187, v188, v185
	v_fma_f32 v184, -v184, v187, v186
	v_div_fmas_f32 v184, v184, v185, v187
	v_div_fixup_f32 v33, v184, v33, 1.0
	global_store_dword v[180:181], v33, off offset:320
	v_mul_f32_e32 v34, v34, v174
	v_mul_f32_e32 v34, 0xbfb8aa3b, v34
	v_exp_f32_e32 v34, v34
	s_nop 0
	v_add_f32_e32 v34, 1.0, v34
	v_div_scale_f32 v184, s[64:65], v34, v34, 1.0
	v_rcp_f32_e32 v185, v184
	s_nop 0
	v_fma_f32 v186, -v184, v185, 1.0
	v_fmac_f32_e32 v185, v186, v185
	v_div_scale_f32 v186, vcc, 1.0, v34, 1.0
	v_mul_f32_e32 v187, v186, v185
	v_fma_f32 v188, -v184, v187, v186
	v_fmac_f32_e32 v187, v188, v185
	v_fma_f32 v184, -v184, v187, v186
	v_div_fmas_f32 v184, v184, v185, v187
	v_div_fixup_f32 v34, v184, v34, 1.0
	global_store_dword v[180:181], v34, off offset:512
	v_mul_f32_e32 v35, v35, v175
	v_mul_f32_e32 v35, 0xbfb8aa3b, v35
	v_exp_f32_e32 v35, v35
	s_nop 0
	v_add_f32_e32 v35, 1.0, v35
	v_div_scale_f32 v184, s[64:65], v35, v35, 1.0
	v_rcp_f32_e32 v185, v184
	s_nop 0
	v_fma_f32 v186, -v184, v185, 1.0
	v_fmac_f32_e32 v185, v186, v185
	v_div_scale_f32 v186, vcc, 1.0, v35, 1.0
	v_mul_f32_e32 v187, v186, v185
	v_fma_f32 v188, -v184, v187, v186
	v_fmac_f32_e32 v187, v188, v185
	v_fma_f32 v184, -v184, v187, v186
	v_div_fmas_f32 v184, v184, v185, v187
	v_div_fixup_f32 v35, v184, v35, 1.0
	global_store_dword v[180:181], v35, off offset:704
	s_add_u32 s60, s60, s61
	s_branch .Lgate_loop
.Lgate_skip:
	s_cmp_gt_i32 s38, 31
	v_readfirstlane_b32 s4, v8
	s_cbranch_scc1 .LBB0_1279
	s_ashr_i32 s5, s38, 31
	s_lshr_b32 s6, s5, 29
	s_add_i32 s6, s38, s6
	s_and_b32 s7, s6, -8
	s_sub_i32 s7, s38, s7
	s_cmp_gt_i32 s7, -1
	s_cbranch_scc0 .LBB0_1262
	s_lshl_b32 s9, s7, 2
	s_cbranch_execz .LBB0_1263
	s_branch .LBB0_1264

.Lpoll_done_s1:
.Las_s1_go:
	v_add_u32_e32 v118, s75, v183
	v_add_u32_e32 v119, v118, v174
	v_add_u32_e32 v118, v118, v171
	s_waitcnt vmcnt(0)
	ds_write_b128 v118, v[102:105]
	ds_write_b128 v118, v[106:109] offset:18432
	ds_write_b128 v119, v[110:113]
	ds_write_b128 v119, v[114:117] offset:18432
	s_waitcnt lgkmcnt(0)
	s_mov_b64 exec, 1
	ds_add_u32 v231, v230 offset:4
	s_mov_b64 exec, -1
	s_add_i32 s79, s54, 2
	s_cmp_le_u32 s79, s46
	s_cbranch_scc0 .Las_nostage
	v_lshl_add_u64 v[102:103], v[152:153], 0, v[134:135]
	v_add_co_u32_e32 v104, vcc, 0xe108000, v102
	v_lshl_add_u64 v[110:111], v[154:155], 0, v[134:135]
	v_addc_co_u32_e32 v105, vcc, 0, v103, vcc
	v_add_co_u32_e32 v106, vcc, 0xf108000, v102
	s_nop 1
	v_addc_co_u32_e32 v107, vcc, 0, v103, vcc
	v_add_co_u32_e32 v112, vcc, 0xe108000, v110
	global_load_dwordx4 v[102:105], v[104:105], off
	s_nop 1
	global_load_dwordx4 v[106:109], v[106:107], off
	v_addc_co_u32_e32 v113, vcc, 0, v111, vcc
	v_add_co_u32_e32 v114, vcc, 0xf108000, v110
	s_nop 1
	v_addc_co_u32_e32 v115, vcc, 0, v111, vcc
	global_load_dwordx4 v[110:113], v[112:113], off
	s_nop 0
	global_load_dwordx4 v[114:117], v[114:115], off
